# attention unit epilogues: the 16 fin LDS reads of each combine block issued up front (one round trip instead of 5 / 8)
# speedup vs baseline: 1.0028x; 1.0012x over previous
; DI float red4_sum(float v, int lane) { v += lane_get(v, lane ^ 16); v += lane_get(v, lane ^ 32); return v; }
; DI void attn_phase(const Params& p, const int layer, const int wid_s) {
;     ...
;         if (br == 1) {
; #pragma unroll
;           for (int hp = 0; hp < 2; ++hp) {
;             const float lt = red4_sum(l[hp], lane);
;             const float sc = lt > 0.f ? gate[hp][1] / lt : 0.f;
; #pragma unroll
;             for (int dt = 0; dt < 4; ++dt)
; #pragma unroll
;               for (int j = 0; j < 4; ++j) fin[(hp * 16 + dt * 4 + j) * 64] += O[hp][dt][j] * sc;
;           }
.LBB0_370:
	ds_read2st64_b32 v[198:199], v188 offset0:152 offset1:153
	ds_read2st64_b32 v[200:201], v188 offset0:154 offset1:155
	ds_read2st64_b32 v[202:203], v188 offset0:156 offset1:157
	ds_read2st64_b32 v[204:205], v188 offset0:158 offset1:159
	ds_read2st64_b32 v[206:207], v188 offset0:160 offset1:161
	ds_read2st64_b32 v[208:209], v188 offset0:162 offset1:163
	ds_read2st64_b32 v[210:211], v188 offset0:164 offset1:165
	ds_read2st64_b32 v[212:213], v188 offset0:166 offset1:167
	ds_read2st64_b32 v[214:215], v188 offset0:168 offset1:169
	ds_read2st64_b32 v[216:217], v188 offset0:170 offset1:171
	ds_read2st64_b32 v[218:219], v188 offset0:172 offset1:173
	ds_read2st64_b32 v[220:221], v188 offset0:174 offset1:175
	ds_read2st64_b32 v[222:223], v188 offset0:176 offset1:177
	ds_read2st64_b32 v[224:225], v188 offset0:178 offset1:179
	ds_read2st64_b32 v[226:227], v188 offset0:180 offset1:181
	ds_read2st64_b32 v[228:229], v188 offset0:182 offset1:183
	ds_bpermute_b32 v6, v179, v2
	ds_bpermute_b32 v7, v179, v3
	s_waitcnt lgkmcnt(0)
	v_pk_add_f32 v[6:7], v[2:3], v[6:7]
	ds_bpermute_b32 v60, v180, v6
	ds_bpermute_b32 v61, v180, v7
	s_waitcnt lgkmcnt(0)
	v_pk_add_f32 v[6:7], v[6:7], v[60:61]
	s_nop 0
	v_div_scale_f32 v0, s[6:7], v6, v6, v189
	v_rcp_f32_e32 v80, v0
	s_nop 0
	v_fma_f32 v81, -v0, v80, 1.0
	v_fmac_f32_e32 v80, v81, v80
	v_div_scale_f32 v81, vcc, v189, v6, v189
	v_mul_f32_e32 v82, v81, v80
	v_fma_f32 v83, -v0, v82, v81
	v_fmac_f32_e32 v82, v83, v80
	v_fma_f32 v0, -v0, v82, v81
	v_div_fmas_f32 v0, v0, v80, v82
	v_div_fixup_f32 v0, v0, v6, v189
	v_cmp_lt_f32_e32 vcc, 0, v6
	s_nop 1
	v_cndmask_b32_e32 v0, 0, v0, vcc
	v_fma_f32 v6, v64, v0, v198
	v_fmac_f32_e32 v199, v65, v0
	ds_write2st64_b32 v188, v6, v199 offset0:152 offset1:153
	v_fma_f32 v6, v66, v0, v200
	v_fmac_f32_e32 v201, v67, v0
	ds_write2st64_b32 v188, v6, v201 offset0:154 offset1:155
	v_fma_f32 v6, v56, v0, v202
	v_fmac_f32_e32 v203, v57, v0
	ds_write2st64_b32 v188, v6, v203 offset0:156 offset1:157
	v_fma_f32 v6, v58, v0, v204
	v_fmac_f32_e32 v205, v59, v0
	ds_write2st64_b32 v188, v6, v205 offset0:158 offset1:159
	v_fma_f32 v6, v52, v0, v206
	v_fmac_f32_e32 v207, v53, v0
	ds_write2st64_b32 v188, v6, v207 offset0:160 offset1:161
	v_fma_f32 v6, v54, v0, v208
	v_fmac_f32_e32 v209, v55, v0
	ds_write2st64_b32 v188, v6, v209 offset0:162 offset1:163
	v_fma_f32 v6, v48, v0, v210
	v_fmac_f32_e32 v211, v49, v0
	ds_write2st64_b32 v188, v6, v211 offset0:164 offset1:165
	v_div_scale_f32 v6, s[6:7], v7, v7, v191
	v_rcp_f32_e32 v60, v6
	v_fma_f32 v61, v50, v0, v212
	v_fmac_f32_e32 v213, v51, v0
	ds_write2st64_b32 v188, v61, v213 offset0:166 offset1:167
	v_fma_f32 v0, -v6, v60, 1.0
	v_fmac_f32_e32 v60, v0, v60
	v_div_scale_f32 v0, vcc, v191, v7, v191
	v_mul_f32_e32 v61, v0, v60
	v_fma_f32 v62, -v6, v61, v0
	v_fmac_f32_e32 v61, v62, v60
	v_fma_f32 v0, -v6, v61, v0
	v_div_fmas_f32 v0, v0, v60, v61
	v_div_fixup_f32 v0, v0, v7, v191
	v_cmp_lt_f32_e32 vcc, 0, v7
	s_nop 1
	v_cndmask_b32_e32 v0, 0, v0, vcc
	v_fma_f32 v6, v46, v0, v216
	v_fmac_f32_e32 v217, v47, v0
	ds_write2st64_b32 v188, v6, v217 offset0:170 offset1:171
	v_fma_f32 v6, v40, v0, v218
	v_fmac_f32_e32 v219, v41, v0
	v_fma_f32 v60, v44, v0, v214
	v_fmac_f32_e32 v215, v45, v0
	ds_write2st64_b32 v188, v6, v219 offset0:172 offset1:173
	ds_write2st64_b32 v188, v60, v215 offset0:168 offset1:169
	v_fma_f32 v60, v42, v0, v220
	v_fmac_f32_e32 v221, v43, v0
	ds_write2st64_b32 v188, v60, v221 offset0:174 offset1:175
	v_fma_f32 v6, v36, v0, v222
	v_fmac_f32_e32 v223, v37, v0
	ds_write2st64_b32 v188, v6, v223 offset0:176 offset1:177
	v_fma_f32 v6, v38, v0, v224
	v_fmac_f32_e32 v225, v39, v0
	ds_write2st64_b32 v188, v6, v225 offset0:178 offset1:179
	v_fma_f32 v6, v32, v0, v226
	v_fmac_f32_e32 v227, v33, v0
	ds_write2st64_b32 v188, v6, v227 offset0:180 offset1:181
	v_fma_f32 v6, v34, v0, v228
	v_fmac_f32_e32 v229, v35, v0
	ds_write2st64_b32 v188, v6, v229 offset0:182 offset1:183
	s_cbranch_execnz .LBB0_336
; DI float red4_sum(float v, int lane) { v += lane_get(v, lane ^ 16); v += lane_get(v, lane ^ 32); return v; }
; DI void attn_phase(const Params& p, const int layer, const int wid_s) {
;     ...
;         } else {
;           int t_late = t; asm volatile("" : "+v"(t_late));
; #pragma unroll
;           for (int hp = 0; hp < 2; ++hp) {
;             const float lt = red4_sum(l[hp], lane);
;             const float sc = lt > 0.f ? gate[hp][2] / lt : 0.f;
; #pragma unroll
;             for (int dt = 0; dt < 4; ++dt) {
;               half4 o;
; #pragma unroll
;               for (int j = 0; j < 4; ++j) o[j] = (h16)(fin[(hp * 16 + dt * 4 + j) * 64] + O[hp][dt][j] * sc);
;               *(half4*)(mix + ((size_t)b * SEQ + t_late) * 1024 + 256 + (hh0 + hp) * 64 + dt * 16 + fq * 4) = o;
;             }
;           }
.LBB0_371:
	ds_read2st64_b32 v[198:199], v188 offset0:152 offset1:153
	ds_read2st64_b32 v[200:201], v188 offset0:154 offset1:155
	ds_read2st64_b32 v[202:203], v188 offset0:156 offset1:157
	ds_read2st64_b32 v[204:205], v188 offset0:158 offset1:159
	ds_read2st64_b32 v[206:207], v188 offset0:160 offset1:161
	ds_read2st64_b32 v[208:209], v188 offset0:162 offset1:163
	ds_read2st64_b32 v[210:211], v188 offset0:164 offset1:165
	ds_read2st64_b32 v[212:213], v188 offset0:166 offset1:167
	ds_read2st64_b32 v[214:215], v188 offset0:168 offset1:169
	ds_read2st64_b32 v[216:217], v188 offset0:170 offset1:171
	ds_read2st64_b32 v[218:219], v188 offset0:172 offset1:173
	ds_read2st64_b32 v[220:221], v188 offset0:174 offset1:175
	ds_read2st64_b32 v[222:223], v188 offset0:176 offset1:177
	ds_read2st64_b32 v[224:225], v188 offset0:178 offset1:179
	ds_read2st64_b32 v[226:227], v188 offset0:180 offset1:181
	ds_read2st64_b32 v[228:229], v188 offset0:182 offset1:183
	ds_bpermute_b32 v6, v179, v2
	ds_bpermute_b32 v7, v179, v3
	v_mov_b32_e32 v60, v187
	v_mov_b32_e32 v151, v1
	v_ashrrev_i32_e32 v61, 31, v60
	s_waitcnt lgkmcnt(0)
	v_pk_add_f32 v[2:3], v[2:3], v[6:7]
	ds_bpermute_b32 v6, v180, v2
	ds_bpermute_b32 v7, v180, v3
	v_lshlrev_b64 v[60:61], 11, v[60:61]
	v_lshl_add_u64 v[60:61], s[0:1], 0, v[60:61]
	v_lshl_add_u64 v[60:61], v[60:61], 0, v[150:151]
	s_mov_b64 s[6:7], 0xd20e200
	s_waitcnt lgkmcnt(0)
	v_pk_add_f32 v[2:3], v[2:3], v[6:7]
	v_lshl_add_u64 v[60:61], v[60:61], 0, s[6:7]
	v_div_scale_f32 v0, s[6:7], v2, v2, v190
	v_rcp_f32_e32 v70, v0
	v_lshl_add_u64 v[6:7], s[26:27], 1, v[60:61]
	v_fma_f32 v71, -v0, v70, 1.0
	v_fmac_f32_e32 v70, v71, v70
	v_div_scale_f32 v71, vcc, v190, v2, v190
	v_mul_f32_e32 v72, v71, v70
	v_fma_f32 v73, -v0, v72, v71
	v_fmac_f32_e32 v72, v73, v70
	v_fma_f32 v0, -v0, v72, v71
	v_div_fmas_f32 v0, v0, v70, v72
	v_div_fixup_f32 v0, v0, v2, v190
	v_cmp_lt_f32_e32 vcc, 0, v2
	v_div_scale_f32 v2, s[6:7], v3, v3, v192
	s_nop 0
	v_cndmask_b32_e32 v0, 0, v0, vcc
	v_pk_fma_f32 v[62:63], v[64:65], v[0:1], v[198:199] op_sel_hi:[1,0,1]
	v_pk_fma_f32 v[64:65], v[66:67], v[0:1], v[200:201] op_sel_hi:[1,0,1]
	v_cvt_pk_f16_f32 v62, v62, v63
	v_cvt_pk_f16_f32 v63, v64, v65
	flat_store_dwordx2 v[6:7], v[62:63]
	s_nop 1
	v_pk_fma_f32 v[56:57], v[56:57], v[0:1], v[202:203] op_sel_hi:[1,0,1]
	v_pk_fma_f32 v[58:59], v[58:59], v[0:1], v[204:205] op_sel_hi:[1,0,1]
	v_cvt_pk_f16_f32 v56, v56, v57
	v_cvt_pk_f16_f32 v57, v58, v59
	flat_store_dwordx2 v[6:7], v[56:57] offset:32
	s_nop 1
	v_pk_fma_f32 v[52:53], v[52:53], v[0:1], v[206:207] op_sel_hi:[1,0,1]
	v_pk_fma_f32 v[54:55], v[54:55], v[0:1], v[208:209] op_sel_hi:[1,0,1]
	v_cvt_pk_f16_f32 v52, v52, v53
	v_cvt_pk_f16_f32 v53, v54, v55
	flat_store_dwordx2 v[6:7], v[52:53] offset:64
	s_nop 1
	v_pk_fma_f32 v[48:49], v[48:49], v[0:1], v[210:211] op_sel_hi:[1,0,1]
	v_rcp_f32_e32 v52, v2
	v_pk_fma_f32 v[50:51], v[50:51], v[0:1], v[212:213] op_sel_hi:[1,0,1]
	v_cvt_pk_f16_f32 v48, v48, v49
	v_cvt_pk_f16_f32 v49, v50, v51
	v_fma_f32 v0, -v2, v52, 1.0
	v_fmac_f32_e32 v52, v0, v52
	v_div_scale_f32 v0, vcc, v192, v3, v192
	flat_store_dwordx2 v[6:7], v[48:49] offset:96
	s_nop 1
	v_mul_f32_e32 v6, v0, v52
	v_fma_f32 v7, -v2, v6, v0
	v_fmac_f32_e32 v6, v7, v52
	v_fma_f32 v0, -v2, v6, v0
	v_div_fmas_f32 v0, v0, v52, v6
	v_div_fixup_f32 v0, v0, v3, v192
	v_cmp_lt_f32_e32 vcc, 0, v3
	v_lshl_add_u64 v[2:3], s[48:49], 1, v[60:61]
	s_nop 0
	v_cndmask_b32_e32 v0, 0, v0, vcc
	v_pk_fma_f32 v[6:7], v[44:45], v[0:1], v[214:215] op_sel_hi:[1,0,1]
	v_pk_fma_f32 v[44:45], v[46:47], v[0:1], v[216:217] op_sel_hi:[1,0,1]
	v_cvt_pk_f16_f32 v6, v6, v7
	v_cvt_pk_f16_f32 v7, v44, v45
	flat_store_dwordx2 v[2:3], v[6:7]
	s_nop 1
	v_pk_fma_f32 v[6:7], v[40:41], v[0:1], v[218:219] op_sel_hi:[1,0,1]
	v_pk_fma_f32 v[40:41], v[42:43], v[0:1], v[220:221] op_sel_hi:[1,0,1]
	v_cvt_pk_f16_f32 v6, v6, v7
	v_cvt_pk_f16_f32 v7, v40, v41
	flat_store_dwordx2 v[2:3], v[6:7] offset:32
	s_nop 1
	v_pk_fma_f32 v[6:7], v[36:37], v[0:1], v[222:223] op_sel_hi:[1,0,1]
	v_pk_fma_f32 v[36:37], v[38:39], v[0:1], v[224:225] op_sel_hi:[1,0,1]
	v_cvt_pk_f16_f32 v6, v6, v7
	v_cvt_pk_f16_f32 v7, v36, v37
	flat_store_dwordx2 v[2:3], v[6:7] offset:64
	s_nop 1
	v_pk_fma_f32 v[6:7], v[32:33], v[0:1], v[226:227] op_sel_hi:[1,0,1]
	v_pk_fma_f32 v[32:33], v[34:35], v[0:1], v[228:229] op_sel_hi:[1,0,1]
	v_cvt_pk_f16_f32 v6, v6, v7
	v_cvt_pk_f16_f32 v7, v32, v33
	flat_store_dwordx2 v[2:3], v[6:7] offset:96
	s_nop 1
	s_branch .LBB0_336
